# FFN-up epilogue of the sample tiles (last round): conv-state rows of all 16 conv steps touched once at the top (dummy loads, lanes t<=1) so the per-step loads hit in L2
# baseline (speedup 1.0000x reference)
;     __device__ __forceinline__ void operator()(f32x4 (&acc)[2][2][4][2], const pg8::Unit& u, int wr, int wc, int fr, int fq) const {
;         const int row0 = u.pm * 256 + wr * 64 + fr, cl0 = wc * 32 + 8 * fq, ch0 = u.pn * 128 + cl0;
;         float sc[2][4];
; #pragma unroll
;         for (int ai = 0; ai < 2; ++ai)
; #pragma unroll
;             for (int m = 0; m < 4; ++m) sc[ai][m] = rf[row0 + ai * 128 + m * 16];
;         {
;             f32x4 sw[2][2];
; #pragma unroll
;             for (int bj = 0; bj < 2; ++bj)
; #pragma unroll
;                 for (int n = 0; n < 2; ++n) { const u32x4 c = *(const u32x4*)(cmax + u.pn * 256 + bj * 128 + cl0 + 4 * n); sw[bj][n] = (f32x4){__uint_as_float(c.x), __uint_as_float(c.y), __uint_as_float(c.z), __uint_as_float(c.w)} * (1.004f / 127.0f); }
; #pragma unroll
;             for (int ai = 0; ai < 2; ++ai)
; #pragma unroll
;                 for (int m = 0; m < 4; ++m)
; #pragma unroll
;                     for (int bj = 0; bj < 2; ++bj)
; #pragma unroll
;                         for (int n = 0; n < 2; ++n) { const i32x4 q = __builtin_bit_cast(i32x4, acc[ai][bj][m][n]); acc[ai][bj][m][n] = (f32x4){(float)q[0], (float)q[1], (float)q[2], (float)q[3]} * sw[bj][n] * sc[ai][m]; }
;         }
;         if ((u.pm & 7) == 7 || u.pm >= MP / 256) {
;     ...
;                     else { const int t = fr & 3; const float* sp = stf + (size_t)((row - MP) >> 2) * 2 * DFF + ch0 + 4 * n;
;                         f32x4 b0 = (f32x4){0.f, 0.f, 0.f, 0.f}, b1 = b0; if (t == 0) b0 = *(const f32x4*)sp; if (t <= 1) b1 = *(const f32x4*)(sp + DFF);
.LBB0_2523:
	s_cmp_lt_i32 s64, 32
	s_cbranch_scc1 .Lf8_entry
	v_readlane_b32 s52, v254, 14
	v_readlane_b32 s53, v254, 15
	v_and_b32_e32 v156, 3, v232
	v_cmp_gt_u32_e64 s[20:21], 2, v156
	s_add_i32 s3, s64, 0xffffffe0
	s_lshl_b32 s3, s3, 6
	s_lshr_b32 s33, s86, 2
	s_add_i32 s3, s3, s33
	v_lshrrev_b32_e32 v157, 2, v232
	v_add_u32_e32 v157, s3, v157
	v_mul_u32_u24_e32 v157, 0x18000, v157
	s_lshl_b32 s3, s2, 9
	v_lshl_add_u32 v158, v242, 2, s3
	v_add_u32_e32 v157, v157, v158
	s_add_u32 s54, s52, 0xc000
	s_addc_u32 s55, s53, 0
	s_and_saveexec_b64 s[40:41], s[20:21]
	v_mov_b32_e32 v159, v157
	global_load_dwordx4 v[152:155], v159, s[52:53]
	global_load_dwordx4 v[152:155], v159, s[52:53] offset:16
	global_load_dwordx4 v[152:155], v159, s[54:55]
	global_load_dwordx4 v[152:155], v159, s[54:55] offset:16
	v_add_u32_e32 v160, 0x60000, v157
	global_load_dwordx4 v[152:155], v160, s[52:53]
	global_load_dwordx4 v[152:155], v160, s[52:53] offset:16
	global_load_dwordx4 v[152:155], v160, s[54:55]
	global_load_dwordx4 v[152:155], v160, s[54:55] offset:16
	v_add_u32_e32 v159, 0xc0000, v157
	global_load_dwordx4 v[152:155], v159, s[52:53]
	global_load_dwordx4 v[152:155], v159, s[52:53] offset:16
	global_load_dwordx4 v[152:155], v159, s[54:55]
	global_load_dwordx4 v[152:155], v159, s[54:55] offset:16
	v_add_u32_e32 v160, 0x120000, v157
	global_load_dwordx4 v[152:155], v160, s[52:53]
	global_load_dwordx4 v[152:155], v160, s[52:53] offset:16
	global_load_dwordx4 v[152:155], v160, s[54:55]
	global_load_dwordx4 v[152:155], v160, s[54:55] offset:16
	v_add_u32_e32 v159, 0x300000, v157
	global_load_dwordx4 v[152:155], v159, s[52:53]
	global_load_dwordx4 v[152:155], v159, s[52:53] offset:16
	global_load_dwordx4 v[152:155], v159, s[54:55]
	global_load_dwordx4 v[152:155], v159, s[54:55] offset:16
	v_add_u32_e32 v160, 0x360000, v157
	global_load_dwordx4 v[152:155], v160, s[52:53]
	global_load_dwordx4 v[152:155], v160, s[52:53] offset:16
	global_load_dwordx4 v[152:155], v160, s[54:55]
	global_load_dwordx4 v[152:155], v160, s[54:55] offset:16
	v_add_u32_e32 v159, 0x3c0000, v157
	global_load_dwordx4 v[152:155], v159, s[52:53]
	global_load_dwordx4 v[152:155], v159, s[52:53] offset:16
	global_load_dwordx4 v[152:155], v159, s[54:55]
	global_load_dwordx4 v[152:155], v159, s[54:55] offset:16
	v_add_u32_e32 v160, 0x420000, v157
	global_load_dwordx4 v[152:155], v160, s[52:53]
	global_load_dwordx4 v[152:155], v160, s[52:53] offset:16
	global_load_dwordx4 v[152:155], v160, s[54:55]
	global_load_dwordx4 v[152:155], v160, s[54:55] offset:16
	s_mov_b64 exec, s[40:41]
	s_lshl_b32 s3, s64, 8
	s_add_i32 s3, s3, s86
	s_lshl_b32 s20, s2, 8
	v_or_b32_e32 v200, s3, v232
	s_ashr_i32 s21, s20, 31
	v_or_b32_e32 v222, 16, v200
	v_lshl_add_u64 v[138:139], s[20:21], 2, v[178:179]
	v_ashrrev_i32_e32 v201, 31, v200
	v_ashrrev_i32_e32 v223, 31, v222
	v_or_b32_e32 v220, 32, v200
	global_load_dwordx4 v[130:133], v[138:139], off
	global_load_dwordx4 v[134:137], v[138:139], off offset:16
	v_lshl_add_u64 v[142:143], v[200:201], 2, s[26:27]
	v_lshl_add_u64 v[140:141], v[222:223], 2, s[26:27]
	v_ashrrev_i32_e32 v221, 31, v220
	v_or_b32_e32 v218, 48, v200
	global_load_dword v212, v[142:143], off
	global_load_dword v210, v[140:141], off
	v_lshl_add_u64 v[140:141], v[220:221], 2, s[26:27]
	v_ashrrev_i32_e32 v219, 31, v218
	global_load_dword v208, v[140:141], off
	global_load_dword v198, v[142:143], off offset:512
	v_lshl_add_u64 v[140:141], v[218:219], 2, s[26:27]
	global_load_dword v206, v[140:141], off
	global_load_dword v196, v[142:143], off offset:576
	v_cvt_f32_i32_e32 v145, v107
	v_cvt_f32_i32_e32 v144, v106
	v_cvt_f32_i32_e32 v147, v109
	v_cvt_f32_i32_e32 v146, v108
	global_load_dwordx4 v[106:109], v[138:139], off offset:528
	s_nop 0
	global_load_dwordx4 v[138:141], v[138:139], off offset:512
	s_nop 0
	global_load_dword v192, v[142:143], off offset:640
	global_load_dword v190, v[142:143], off offset:704
	v_cvt_f32_i32_e32 v115, v115
	v_cvt_f32_i32_e32 v114, v114
	v_cvt_f32_i32_e32 v127, v127
	v_cvt_f32_i32_e32 v126, v126
	v_cvt_f32_i32_e32 v117, v117
	v_cvt_f32_i32_e32 v116, v116
	v_cvt_f32_i32_e32 v95, v95
	v_cvt_f32_i32_e32 v94, v94
	v_cvt_f32_i32_e32 v149, v87
	v_cvt_f32_i32_e32 v148, v86
	v_cvt_f32_i32_e32 v151, v89
	v_cvt_f32_i32_e32 v150, v88
	v_cvt_f32_i32_e32 v129, v129
	v_cvt_f32_i32_e32 v128, v128
	v_cvt_f32_i32_e32 v97, v97
	v_cvt_f32_i32_e32 v96, v96
	v_cvt_f32_i32_e32 v63, v63
	v_cvt_f32_i32_e32 v65, v65
	v_cvt_f32_i32_e32 v64, v64
	v_cvt_f32_i32_e32 v62, v62
	v_cvt_f32_i32_e32 v55, v55
	v_cvt_f32_i32_e32 v57, v57
	v_cvt_f32_i32_e32 v56, v56
	v_cvt_f32_i32_e32 v54, v54
	s_and_b32 s33, s64, 7
	v_cvt_f32_i32_e32 v51, v51
	v_cvt_f32_i32_e32 v53, v53
	v_cvt_f32_i32_e32 v52, v52
	v_cvt_f32_i32_e32 v50, v50
	s_cmp_eq_u32 s33, 7
	v_cvt_f32_i32_e32 v123, v123
	v_cvt_f32_i32_e32 v122, v122
	v_cvt_f32_i32_e32 v125, v125
	v_cvt_f32_i32_e32 v124, v124
	v_cvt_f32_i32_e32 v103, v103
	v_cvt_f32_i32_e32 v102, v102
	v_cvt_f32_i32_e32 v105, v105
	v_cvt_f32_i32_e32 v104, v104
	v_cvt_f32_i32_e32 v79, v79
	v_cvt_f32_i32_e32 v81, v81
	v_cvt_f32_i32_e32 v80, v80
	v_cvt_f32_i32_e32 v78, v78
	v_cvt_f32_i32_e32 v71, v71
	v_cvt_f32_i32_e32 v73, v73
	v_cvt_f32_i32_e32 v72, v72
	v_cvt_f32_i32_e32 v70, v70
	v_cvt_f32_i32_e32 v19, v19
	v_cvt_f32_i32_e32 v21, v21
	v_cvt_f32_i32_e32 v20, v20
	v_cvt_f32_i32_e32 v18, v18
	s_cselect_b64 s[66:67], -1, 0
	s_cmp_lg_u32 s33, 7
	s_cselect_b64 s[68:69], -1, 0
	s_cmp_lt_i32 s64, 32
	s_cselect_b64 s[62:63], -1, 0
	s_cmp_gt_i32 s64, 31
	s_cselect_b64 s[20:21], -1, 0
	v_lshl_or_b32 v194, s2, 7, v242
	s_or_b64 s[20:21], s[20:21], s[66:67]
	v_add_u32_e32 v219, 0x80, v200
	s_waitcnt vmcnt(0)
;     __device__ __forceinline__ void operator()(f32x4 (&acc)[2][2][4][2], const pg8::Unit& u, int wr, int wc, int fr, int fq) const {
;     ...
;                 for (int n = 0; n < 2; ++n) { const u32x4 c = *(const u32x4*)(cmax + u.pn * 256 + bj * 128 + cl0 + 4 * n); sw[bj][n] = (f32x4){__uint_as_float(c.x), __uint_as_float(c.y), __uint_as_float(c.z), __uint_as_float(c.w)} * (1.004f / 127.0f); }
; #pragma unroll
;             for (int ai = 0; ai < 2; ++ai)
; #pragma unroll
;                 for (int m = 0; m < 4; ++m)
; #pragma unroll
;                     for (int bj = 0; bj < 2; ++bj)
; #pragma unroll
;                         for (int n = 0; n < 2; ++n) { const i32x4 q = __builtin_bit_cast(i32x4, acc[ai][bj][m][n]); acc[ai][bj][m][n] = (f32x4){(float)q[0], (float)q[1], (float)q[2], (float)q[3]} * sw[bj][n] * sc[ai][m]; }
;         }
;         if ((u.pm & 7) == 7 || u.pm >= MP / 256) {
; #pragma unroll
;             for (int ai = 0; ai < 2; ++ai)
; #pragma unroll
;                 for (int m = 0; m < 4; ++m) { const int row = row0 + ai * 128 + m * 16; float* so = nullptr;
;                     if (row < MP) { const int t = row & (SEQ - 1); if (t >= SEQ - 2) so = out + O_PFC + ((size_t)(row >> 11) * 2 + (t - (SEQ - 2))) * DFF + ch0; }
;                     else { const int r = row - MP, t = r & 3; if (t >= 2) so = out + O_SFC + ((size_t)(r >> 2) * 2 + (t - 2)) * DFF + ch0; }
;                     if (so) { *(f32x4*)so = acc[ai][0][m][0]; *(f32x4*)(so + 4) = acc[ai][0][m][1]; } } }
	v_pk_mul_f32 v[130:131], v[130:131], s[0:1] op_sel_hi:[1,0]
	v_pk_mul_f32 v[152:153], v[134:135], s[0:1] op_sel_hi:[1,0]
	v_pk_mul_f32 v[132:133], v[132:133], s[0:1] op_sel_hi:[1,0]
	v_pk_mul_f32 v[142:143], v[136:137], s[0:1] op_sel_hi:[1,0]
	v_pk_mul_f32 v[114:115], v[130:131], v[114:115]
	v_pk_mul_f32 v[144:145], v[152:153], v[144:145]
	v_pk_mul_f32 v[88:89], v[130:131], v[126:127]
	v_pk_mul_f32 v[116:117], v[132:133], v[116:117]
	v_pk_mul_f32 v[146:147], v[142:143], v[146:147]
	v_pk_mul_f32 v[160:161], v[152:153], v[94:95]
	v_pk_mul_f32 v[126:127], v[210:211], v[114:115] op_sel_hi:[0,1]
	v_pk_mul_f32 v[94:95], v[210:211], v[144:145] op_sel_hi:[0,1]
	v_pk_mul_f32 v[114:115], v[132:133], v[150:151]
	v_pk_mul_f32 v[144:145], v[130:131], v[148:149]
	v_pk_mul_f32 v[86:87], v[132:133], v[128:129]
	v_pk_mul_f32 v[158:159], v[142:143], v[96:97]
	v_pk_mul_f32 v[128:129], v[210:211], v[116:117] op_sel_hi:[0,1]
	v_pk_mul_f32 v[96:97], v[210:211], v[146:147] op_sel_hi:[0,1]
	v_pk_mul_f32 v[116:117], v[206:207], v[114:115] op_sel_hi:[0,1]
	v_pk_mul_f32 v[114:115], v[206:207], v[144:145] op_sel_hi:[0,1]
	v_cvt_f32_i32_e32 v145, v39
	v_cvt_f32_i32_e32 v147, v41
	v_cvt_f32_i32_e32 v146, v40
	v_cvt_f32_i32_e32 v144, v38
	v_pk_mul_f32 v[64:65], v[142:143], v[64:65]
	v_pk_mul_f32 v[62:63], v[152:153], v[62:63]
	v_pk_mul_f32 v[40:41], v[198:199], v[64:65] op_sel_hi:[0,1]
	v_pk_mul_f32 v[38:39], v[198:199], v[62:63] op_sel_hi:[0,1]
	v_pk_mul_f32 v[64:65], v[132:133], v[146:147]
	v_pk_mul_f32 v[62:63], v[130:131], v[144:145]
	v_cvt_f32_i32_e32 v145, v31
	v_cvt_f32_i32_e32 v147, v33
	v_cvt_f32_i32_e32 v146, v32
	v_cvt_f32_i32_e32 v144, v30
	v_pk_mul_f32 v[56:57], v[142:143], v[56:57]
	v_pk_mul_f32 v[54:55], v[152:153], v[54:55]
	v_pk_mul_f32 v[32:33], v[196:197], v[56:57] op_sel_hi:[0,1]
	v_pk_mul_f32 v[30:31], v[196:197], v[54:55] op_sel_hi:[0,1]
	v_pk_mul_f32 v[56:57], v[132:133], v[146:147]
	v_pk_mul_f32 v[54:55], v[130:131], v[144:145]
	v_cvt_f32_i32_e32 v145, v27
	v_cvt_f32_i32_e32 v147, v29
	v_cvt_f32_i32_e32 v146, v28
	v_cvt_f32_i32_e32 v144, v26
	v_pk_mul_f32 v[52:53], v[142:143], v[52:53]
	v_pk_mul_f32 v[50:51], v[152:153], v[50:51]
	v_pk_mul_f32 v[124:125], v[142:143], v[124:125]
	v_pk_mul_f32 v[122:123], v[152:153], v[122:123]
	v_pk_mul_f32 v[154:155], v[132:133], v[104:105]
	v_pk_mul_f32 v[156:157], v[130:131], v[102:103]
	v_pk_mul_f32 v[80:81], v[142:143], v[80:81]
	v_pk_mul_f32 v[78:79], v[152:153], v[78:79]
	v_pk_mul_f32 v[72:73], v[132:133], v[72:73]
	v_pk_mul_f32 v[70:71], v[130:131], v[70:71]
	v_pk_mul_f32 v[26:27], v[192:193], v[50:51] op_sel_hi:[0,1]
	v_pk_mul_f32 v[28:29], v[192:193], v[52:53] op_sel_hi:[0,1]
	v_pk_mul_f32 v[52:53], v[132:133], v[146:147]
	v_pk_mul_f32 v[50:51], v[130:131], v[144:145]
	v_pk_mul_f32 v[20:21], v[142:143], v[20:21]
	v_pk_mul_f32 v[18:19], v[152:153], v[18:19]
	v_add_u32_e32 v201, 0xb0, v200
	v_pk_mul_f32 v[134:135], v[212:213], v[88:89] op_sel_hi:[0,1]
	v_pk_mul_f32 v[136:137], v[212:213], v[86:87] op_sel_hi:[0,1]
	v_pk_mul_f32 v[102:103], v[212:213], v[122:123] op_sel_hi:[0,1]
	v_pk_mul_f32 v[104:105], v[212:213], v[124:125] op_sel_hi:[0,1]
	v_pk_mul_f32 v[124:125], v[208:209], v[154:155] op_sel_hi:[0,1]
	v_pk_mul_f32 v[122:123], v[208:209], v[156:157] op_sel_hi:[0,1]
	v_pk_mul_f32 v[88:89], v[208:209], v[158:159] op_sel_hi:[0,1]
	v_pk_mul_f32 v[86:87], v[208:209], v[160:161] op_sel_hi:[0,1]
	v_pk_mul_f32 v[80:81], v[206:207], v[80:81] op_sel_hi:[0,1]
	v_pk_mul_f32 v[78:79], v[206:207], v[78:79] op_sel_hi:[0,1]
	v_pk_mul_f32 v[70:71], v[198:199], v[70:71] op_sel_hi:[0,1]
	v_pk_mul_f32 v[72:73], v[198:199], v[72:73] op_sel_hi:[0,1]
	v_pk_mul_f32 v[62:63], v[196:197], v[62:63] op_sel_hi:[0,1]
	v_pk_mul_f32 v[64:65], v[196:197], v[64:65] op_sel_hi:[0,1]
	v_pk_mul_f32 v[54:55], v[192:193], v[54:55] op_sel_hi:[0,1]
	v_pk_mul_f32 v[56:57], v[192:193], v[56:57] op_sel_hi:[0,1]
	v_pk_mul_f32 v[50:51], v[190:191], v[50:51] op_sel_hi:[0,1]
	v_pk_mul_f32 v[52:53], v[190:191], v[52:53] op_sel_hi:[0,1]
	v_pk_mul_f32 v[18:19], v[190:191], v[18:19] op_sel_hi:[0,1]
	v_pk_mul_f32 v[20:21], v[190:191], v[20:21] op_sel_hi:[0,1]
	s_andn2_b64 vcc, exec, s[20:21]
	v_ashrrev_i32_e32 v195, 31, v194
	s_cbranch_vccnz .LBB0_2557
	v_cmp_lt_i32_e32 vcc, s95, v200
	s_and_b64 s[70:71], vcc, s[36:37]
	v_mov_b64_e32 v[130:131], 0
	s_and_saveexec_b64 s[20:21], s[70:71]
	v_add_u32_e32 v130, 0xffffe000, v200
	v_lshrrev_b32_e32 v130, 1, v130
	v_and_b32_e32 v130, 0x7fffffe6, v130
	v_add_u32_e32 v132, v130, v243
	v_mov_b64_e32 v[130:131], s[34:35]
	v_mad_u64_u32 v[130:131], s[70:71], v132, s94, v[130:131]
	v_lshl_add_u64 v[130:131], v[194:195], 2, v[130:131]
	s_or_b64 exec, exec, s[20:21]
	v_cmp_ne_u64_e32 vcc, 0, v[130:131]
	s_and_saveexec_b64 s[20:21], vcc
	s_cbranch_execz .LBB0_2528
	global_store_dwordx4 v[130:131], v[134:137], off
	global_store_dwordx4 v[130:131], v[102:105], off offset:16
